# P1 main K-loop: LDS-DMA loads use SGPR base + 32-bit VGPR offset (drop 64-bit address VALU)
# speedup vs baseline: 1.0035x; 1.0035x over previous
; #define PG8_STAGE(bufoff, gbase, voff) do { _Pragma("unroll") for (int _i = 0; _i < 2; ++_i) \
;         __builtin_amdgcn_global_load_lds((const unsigned*)((const char*)(gbase) + (voff)[_i]), (LAS unsigned*)(lds + (bufoff) + ldsw + _i * 8192), 16, 0, 0); } while (0)
; #define PG8_LDA(dst, b, h) do { _Pragma("unroll") for (int m = 0; m < 4; ++m) _Pragma("unroll") for (int k = 0; k < 2; ++k) dst[m][k] = *(const LAS bf16x8*)(lds + PG8_SA(b, h) + aoff + m * 2048 + k * 1024); } while (0)
; #define PG8_LDB(dst, b, h) do { _Pragma("unroll") for (int n = 0; n < 2; ++n) _Pragma("unroll") for (int k = 0; k < 2; ++k) dst[n][k] = *(const LAS bf16x8*)(lds + PG8_SB(b, h) + boff + n * 2048 + k * 1024); } while (0)
; #define PG8_MMA(ai, bj, At, Bt) do { __builtin_amdgcn_s_setprio(1); _Pragma("unroll") for (int m = 0; m < 4; ++m) _Pragma("unroll") for (int n = 0; n < 2; ++n) _Pragma("unroll") for (int k = 0; k < 2; ++k) \
;         acc[ai][bj][m][n] = __builtin_amdgcn_mfma_f32_16x16x32_bf16(Bt[n][k], At[m][k], acc[ai][bj][m][n], 0, 0, 0); __builtin_amdgcn_s_setprio(0); } while (0)
; #define PG8_WAIT_V(n) asm volatile("s_waitcnt vmcnt(" #n ")" ::: "memory")
; #define PG8_WAIT_L(n) asm volatile("s_waitcnt lgkmcnt(" #n ")" ::: "memory")
; #define PG8_BAR __builtin_amdgcn_s_barrier()
; #define PG8_SCHED __builtin_amdgcn_sched_barrier(0)
; template <class Epi, bool ALIGN_EPI>
; DI void gemm_phase(const int wv, LAS unsigned char* lds, const GemmD g, const Sched& S, const Epi& E) {
;     ...
;         for (int t = 0; t < nt; t += 2) {
;             const bool last = (t == nt - 2);
;             const char* a1 = cA + (size_t)(t + 1) * kstepA;
;             const char* a2 = last ? nA : cA + (size_t)(t + 2) * kstepA; const char* b2 = last ? nB : cB + (size_t)(t + 2) * kstepB;
;             const char* a3 = a2 + kstepA; const char* b3 = b2 + kstepB;
;             PG8_LDB(B0, 0, 0); PG8_LDB(B1, 0, 1); PG8_SCHED; PG8_LDA(At, 0, 0); PG8_STAGE(PG8_SA(1, 1), a1 + hstepA, voffA);
;             PG8_WAIT_V(8); PG8_WAIT_L(0); PG8_BAR; PG8_MMA(0, 0, At, B0); PG8_MMA(0, 1, At, B1); PG8_BAR; PG8_SCHED;
;             PG8_LDA(At, 0, 1); PG8_STAGE(PG8_SB(0, 0), b2, voffB); PG8_STAGE(PG8_SB(0, 1), b2 + hstepB, voffB); PG8_STAGE(PG8_SA(0, 0), a2, voffA);
;             PG8_WAIT_V(8); PG8_WAIT_L(0); PG8_BAR; PG8_MMA(1, 0, At, B0); PG8_MMA(1, 1, At, B1); PG8_BAR; PG8_SCHED;
.LBB0_244:
	ds_read_b128 v[148:151], v154
	ds_read_b128 v[158:161], v154 offset:1024
	ds_read_b128 v[162:165], v154 offset:2048
	ds_read_b128 v[166:169], v154 offset:3072
	ds_read_b128 v[170:173], v155
	ds_read_b128 v[174:177], v155 offset:1024
	ds_read_b128 v[178:181], v155 offset:2048
	ds_read_b128 v[182:185], v155 offset:3072
	s_add_u32 s40, s58, 0xfffc0080
	s_addc_u32 s41, s59, -1
	s_cmp_eq_u32 s39, 12
	s_cselect_b32 s63, s9, s41
	s_cselect_b32 s62, s10, s40
	s_cselect_b32 s61, s21, s38
	s_cselect_b32 s60, s23, s37
	s_add_i32 m0, s0, 0xc000
	ds_read_b128 v[186:189], v156
	ds_read_b128 v[190:193], v156 offset:1024
	ds_read_b128 v[194:197], v156 offset:2048
	ds_read_b128 v[198:201], v156 offset:3072
	ds_read_b128 v[202:205], v156 offset:4096
	ds_read_b128 v[206:209], v156 offset:5120
	ds_read_b128 v[210:213], v156 offset:6144
	ds_read_b128 v[214:217], v156 offset:7168
	global_load_lds_dwordx4 v140, s[58:59]
	s_add_i32 m0, s0, 0xe000
	s_nop 0
	global_load_lds_dwordx4 v142, s[58:59]
	s_waitcnt vmcnt(8)
	s_waitcnt lgkmcnt(0)
	s_barrier
	s_setprio 1
	s_waitcnt lgkmcnt(0)
	v_mfma_f32_16x16x32_bf16 v[124:127], v[148:151], v[186:189], v[124:127]
	v_mfma_f32_16x16x32_bf16 v[120:123], v[162:165], v[186:189], v[120:123]
	v_mfma_f32_16x16x32_bf16 v[108:111], v[148:151], v[194:197], v[108:111]
	v_mfma_f32_16x16x32_bf16 v[104:107], v[162:165], v[194:197], v[104:107]
	v_mfma_f32_16x16x32_bf16 v[92:95], v[148:151], v[202:205], v[92:95]
	v_mfma_f32_16x16x32_bf16 v[88:91], v[162:165], v[202:205], v[88:91]
	v_mfma_f32_16x16x32_bf16 v[76:79], v[148:151], v[210:213], v[76:79]
	v_mfma_f32_16x16x32_bf16 v[72:75], v[162:165], v[210:213], v[72:75]
	v_mfma_f32_16x16x32_bf16 v[124:127], v[158:161], v[190:193], v[124:127]
	v_mfma_f32_16x16x32_bf16 v[120:123], v[166:169], v[190:193], v[120:123]
	v_mfma_f32_16x16x32_bf16 v[108:111], v[158:161], v[198:201], v[108:111]
	v_mfma_f32_16x16x32_bf16 v[104:107], v[166:169], v[198:201], v[104:107]
	v_mfma_f32_16x16x32_bf16 v[92:95], v[158:161], v[206:209], v[92:95]
	v_mfma_f32_16x16x32_bf16 v[88:91], v[166:169], v[206:209], v[88:91]
	v_mfma_f32_16x16x32_bf16 v[76:79], v[158:161], v[214:217], v[76:79]
	v_mfma_f32_16x16x32_bf16 v[72:75], v[166:169], v[214:217], v[72:75]
	s_setprio 0
	s_setprio 1
	v_mfma_f32_16x16x32_bf16 v[116:119], v[170:173], v[186:189], v[116:119]
	v_mfma_f32_16x16x32_bf16 v[112:115], v[178:181], v[186:189], v[112:115]
	v_mfma_f32_16x16x32_bf16 v[100:103], v[170:173], v[194:197], v[100:103]
	v_mfma_f32_16x16x32_bf16 v[96:99], v[178:181], v[194:197], v[96:99]
	v_mfma_f32_16x16x32_bf16 v[84:87], v[170:173], v[202:205], v[84:87]
	v_mfma_f32_16x16x32_bf16 v[80:83], v[178:181], v[202:205], v[80:83]
	v_mfma_f32_16x16x32_bf16 v[68:71], v[170:173], v[210:213], v[68:71]
	v_mfma_f32_16x16x32_bf16 v[64:67], v[178:181], v[210:213], v[64:67]
	v_mfma_f32_16x16x32_bf16 v[116:119], v[174:177], v[190:193], v[116:119]
	v_mfma_f32_16x16x32_bf16 v[112:115], v[182:185], v[190:193], v[112:115]
	v_mfma_f32_16x16x32_bf16 v[100:103], v[174:177], v[198:201], v[100:103]
	v_mfma_f32_16x16x32_bf16 v[96:99], v[182:185], v[198:201], v[96:99]
	v_mfma_f32_16x16x32_bf16 v[84:87], v[174:177], v[206:209], v[84:87]
	v_mfma_f32_16x16x32_bf16 v[80:83], v[182:185], v[206:209], v[80:83]
	v_mfma_f32_16x16x32_bf16 v[68:71], v[174:177], v[214:217], v[68:71]
	v_mfma_f32_16x16x32_bf16 v[64:67], v[182:185], v[214:217], v[64:67]
	s_setprio 0
	s_barrier
	s_add_i32 s40, s34, s85
	s_mov_b32 m0, s40
	ds_read_b128 v[186:189], v156 offset:16384
	ds_read_b128 v[190:193], v156 offset:17408
	ds_read_b128 v[194:197], v156 offset:18432
	ds_read_b128 v[198:201], v156 offset:19456
	ds_read_b128 v[202:205], v156 offset:20480
	ds_read_b128 v[206:209], v156 offset:21504
	ds_read_b128 v[210:213], v156 offset:22528
	ds_read_b128 v[214:217], v156 offset:23552
	global_load_lds_dwordx4 v130, s[60:61]
	s_add_i32 m0, s40, 0x2000
	s_add_u32 s40, s60, 0x40000
	s_addc_u32 s41, s61, 0
	s_add_i32 s42, s35, s85
	global_load_lds_dwordx4 v134, s[60:61]
	s_mov_b32 m0, s42
	s_nop 0
	global_load_lds_dwordx4 v130, s[40:41]
	s_add_i32 m0, s42, 0x2000
	s_nop 0
	global_load_lds_dwordx4 v134, s[40:41]
	s_mov_b32 m0, s0
	s_nop 0
	global_load_lds_dwordx4 v128, s[62:63]
	s_mov_b32 m0, s1
	s_nop 0
	global_load_lds_dwordx4 v132, s[62:63]
	s_waitcnt vmcnt(8)
	s_waitcnt lgkmcnt(0)
	s_barrier
	s_setprio 1
	s_waitcnt lgkmcnt(0)
	v_mfma_f32_16x16x32_bf16 v[60:63], v[148:151], v[186:189], v[60:63]
	v_mfma_f32_16x16x32_bf16 v[56:59], v[162:165], v[186:189], v[56:59]
	v_mfma_f32_16x16x32_bf16 v[44:47], v[148:151], v[194:197], v[44:47]
	v_mfma_f32_16x16x32_bf16 v[40:43], v[162:165], v[194:197], v[40:43]
	v_mfma_f32_16x16x32_bf16 v[28:31], v[148:151], v[202:205], v[28:31]
	v_mfma_f32_16x16x32_bf16 v[24:27], v[162:165], v[202:205], v[24:27]
	v_mfma_f32_16x16x32_bf16 v[12:15], v[148:151], v[210:213], v[12:15]
	v_mfma_f32_16x16x32_bf16 v[8:11], v[162:165], v[210:213], v[8:11]
	v_mfma_f32_16x16x32_bf16 v[60:63], v[158:161], v[190:193], v[60:63]
	v_mfma_f32_16x16x32_bf16 v[56:59], v[166:169], v[190:193], v[56:59]
	v_mfma_f32_16x16x32_bf16 v[44:47], v[158:161], v[198:201], v[44:47]
	v_mfma_f32_16x16x32_bf16 v[40:43], v[166:169], v[198:201], v[40:43]
	v_mfma_f32_16x16x32_bf16 v[28:31], v[158:161], v[206:209], v[28:31]
	v_mfma_f32_16x16x32_bf16 v[24:27], v[166:169], v[206:209], v[24:27]
	v_mfma_f32_16x16x32_bf16 v[12:15], v[158:161], v[214:217], v[12:15]
	v_mfma_f32_16x16x32_bf16 v[8:11], v[166:169], v[214:217], v[8:11]
	s_setprio 0
	s_setprio 1
	v_mfma_f32_16x16x32_bf16 v[52:55], v[170:173], v[186:189], v[52:55]
	v_mfma_f32_16x16x32_bf16 v[48:51], v[178:181], v[186:189], v[48:51]
	v_mfma_f32_16x16x32_bf16 v[36:39], v[170:173], v[194:197], v[36:39]
	v_mfma_f32_16x16x32_bf16 v[32:35], v[178:181], v[194:197], v[32:35]
	v_mfma_f32_16x16x32_bf16 v[20:23], v[170:173], v[202:205], v[20:23]
	v_mfma_f32_16x16x32_bf16 v[16:19], v[178:181], v[202:205], v[16:19]
	v_mfma_f32_16x16x32_bf16 v[4:7], v[170:173], v[210:213], v[4:7]
	v_mfma_f32_16x16x32_bf16 v[0:3], v[178:181], v[210:213], v[0:3]
	v_mfma_f32_16x16x32_bf16 v[52:55], v[174:177], v[190:193], v[52:55]
	v_mfma_f32_16x16x32_bf16 v[48:51], v[182:185], v[190:193], v[48:51]
	v_mfma_f32_16x16x32_bf16 v[36:39], v[174:177], v[198:201], v[36:39]
	v_mfma_f32_16x16x32_bf16 v[32:35], v[182:185], v[198:201], v[32:35]
	v_mfma_f32_16x16x32_bf16 v[20:23], v[174:177], v[206:209], v[20:23]
	v_mfma_f32_16x16x32_bf16 v[16:19], v[182:185], v[206:209], v[16:19]
	v_mfma_f32_16x16x32_bf16 v[4:7], v[174:177], v[214:217], v[4:7]
	v_mfma_f32_16x16x32_bf16 v[0:3], v[182:185], v[214:217], v[0:3]
	s_setprio 0
	s_barrier
; #define PG8_STAGE(bufoff, gbase, voff) do { _Pragma("unroll") for (int _i = 0; _i < 2; ++_i) \
;         __builtin_amdgcn_global_load_lds((const unsigned*)((const char*)(gbase) + (voff)[_i]), (LAS unsigned*)(lds + (bufoff) + ldsw + _i * 8192), 16, 0, 0); } while (0)
; #define PG8_LDA(dst, b, h) do { _Pragma("unroll") for (int m = 0; m < 4; ++m) _Pragma("unroll") for (int k = 0; k < 2; ++k) dst[m][k] = *(const LAS bf16x8*)(lds + PG8_SA(b, h) + aoff + m * 2048 + k * 1024); } while (0)
; #define PG8_LDB(dst, b, h) do { _Pragma("unroll") for (int n = 0; n < 2; ++n) _Pragma("unroll") for (int k = 0; k < 2; ++k) dst[n][k] = *(const LAS bf16x8*)(lds + PG8_SB(b, h) + boff + n * 2048 + k * 1024); } while (0)
; #define PG8_MMA(ai, bj, At, Bt) do { __builtin_amdgcn_s_setprio(1); _Pragma("unroll") for (int m = 0; m < 4; ++m) _Pragma("unroll") for (int n = 0; n < 2; ++n) _Pragma("unroll") for (int k = 0; k < 2; ++k) \
;         acc[ai][bj][m][n] = __builtin_amdgcn_mfma_f32_16x16x32_bf16(Bt[n][k], At[m][k], acc[ai][bj][m][n], 0, 0, 0); __builtin_amdgcn_s_setprio(0); } while (0)
; #define PG8_WAIT_V(n) asm volatile("s_waitcnt vmcnt(" #n ")" ::: "memory")
; #define PG8_WAIT_L(n) asm volatile("s_waitcnt lgkmcnt(" #n ")" ::: "memory")
; #define PG8_BAR __builtin_amdgcn_s_barrier()
; #define PG8_SCHED __builtin_amdgcn_sched_barrier(0)
; template <class Epi, bool ALIGN_EPI>
; DI void gemm_phase(const int wv, LAS unsigned char* lds, const GemmD g, const Sched& S, const Epi& E) {
;     ...
;             PG8_LDB(B0, 1, 0); PG8_LDB(B1, 1, 1); PG8_SCHED; PG8_LDA(At, 1, 0); PG8_STAGE(PG8_SA(0, 1), a2 + hstepA, voffA);
;             PG8_WAIT_V(8); PG8_WAIT_L(0); PG8_BAR; PG8_MMA(0, 0, At, B0); PG8_MMA(0, 1, At, B1); PG8_BAR; PG8_SCHED;
;             PG8_LDA(At, 1, 1); PG8_STAGE(PG8_SB(1, 0), b3, voffB); PG8_STAGE(PG8_SB(1, 1), b3 + hstepB, voffB); PG8_STAGE(PG8_SA(1, 0), a3, voffA);
;             PG8_WAIT_V(8); PG8_WAIT_L(0); PG8_BAR; PG8_MMA(1, 0, At, B0); PG8_MMA(1, 1, At, B1); PG8_BAR; PG8_SCHED;
;         }
	s_add_i32 s42, 0, 0x18000
	v_add_u32_e32 v136, s42, v152
	s_add_i32 s43, 0, 0x1c000
	ds_read_b128 v[148:151], v136
	ds_read_b128 v[158:161], v136 offset:1024
	ds_read_b128 v[162:165], v136 offset:2048
	ds_read_b128 v[166:169], v136 offset:3072
	v_add_u32_e32 v136, s43, v152
	ds_read_b128 v[170:173], v136
	ds_read_b128 v[174:177], v136 offset:1024
	ds_read_b128 v[178:181], v136 offset:2048
	ds_read_b128 v[182:185], v136 offset:3072
	s_add_u32 s40, s62, 0x40000
	s_addc_u32 s41, s63, 0
	s_mov_b32 m0, s2
	ds_read_b128 v[186:189], v156 offset:32768
	ds_read_b128 v[190:193], v156 offset:33792
	ds_read_b128 v[194:197], v156 offset:34816
	ds_read_b128 v[198:201], v156 offset:35840
	ds_read_b128 v[202:205], v156 offset:36864
	ds_read_b128 v[206:209], v156 offset:37888
	ds_read_b128 v[210:213], v156 offset:38912
	ds_read_b128 v[214:217], v156 offset:39936
	global_load_lds_dwordx4 v128, s[40:41]
	s_mov_b32 m0, s29
	s_nop 0
	global_load_lds_dwordx4 v132, s[40:41]
	s_waitcnt vmcnt(8)
	s_waitcnt lgkmcnt(0)
	s_barrier
	s_setprio 1
	s_waitcnt lgkmcnt(0)
	v_mfma_f32_16x16x32_bf16 v[124:127], v[148:151], v[186:189], v[124:127]
	v_mfma_f32_16x16x32_bf16 v[120:123], v[162:165], v[186:189], v[120:123]
	v_mfma_f32_16x16x32_bf16 v[108:111], v[148:151], v[194:197], v[108:111]
	v_mfma_f32_16x16x32_bf16 v[104:107], v[162:165], v[194:197], v[104:107]
	v_mfma_f32_16x16x32_bf16 v[92:95], v[148:151], v[202:205], v[92:95]
	v_mfma_f32_16x16x32_bf16 v[88:91], v[162:165], v[202:205], v[88:91]
	v_mfma_f32_16x16x32_bf16 v[76:79], v[148:151], v[210:213], v[76:79]
	v_mfma_f32_16x16x32_bf16 v[72:75], v[162:165], v[210:213], v[72:75]
	v_mfma_f32_16x16x32_bf16 v[124:127], v[158:161], v[190:193], v[124:127]
	v_mfma_f32_16x16x32_bf16 v[120:123], v[166:169], v[190:193], v[120:123]
	v_mfma_f32_16x16x32_bf16 v[108:111], v[158:161], v[198:201], v[108:111]
	v_mfma_f32_16x16x32_bf16 v[104:107], v[166:169], v[198:201], v[104:107]
	v_mfma_f32_16x16x32_bf16 v[92:95], v[158:161], v[206:209], v[92:95]
	v_mfma_f32_16x16x32_bf16 v[88:91], v[166:169], v[206:209], v[88:91]
	v_mfma_f32_16x16x32_bf16 v[76:79], v[158:161], v[214:217], v[76:79]
	v_mfma_f32_16x16x32_bf16 v[72:75], v[166:169], v[214:217], v[72:75]
	s_setprio 0
	s_setprio 1
	v_mfma_f32_16x16x32_bf16 v[116:119], v[170:173], v[186:189], v[116:119]
	v_mfma_f32_16x16x32_bf16 v[112:115], v[178:181], v[186:189], v[112:115]
	v_mfma_f32_16x16x32_bf16 v[100:103], v[170:173], v[194:197], v[100:103]
	v_mfma_f32_16x16x32_bf16 v[96:99], v[178:181], v[194:197], v[96:99]
	v_mfma_f32_16x16x32_bf16 v[84:87], v[170:173], v[202:205], v[84:87]
	v_mfma_f32_16x16x32_bf16 v[80:83], v[178:181], v[202:205], v[80:83]
	v_mfma_f32_16x16x32_bf16 v[68:71], v[170:173], v[210:213], v[68:71]
	v_mfma_f32_16x16x32_bf16 v[64:67], v[178:181], v[210:213], v[64:67]
	v_mfma_f32_16x16x32_bf16 v[116:119], v[174:177], v[190:193], v[116:119]
	v_mfma_f32_16x16x32_bf16 v[112:115], v[182:185], v[190:193], v[112:115]
	v_mfma_f32_16x16x32_bf16 v[100:103], v[174:177], v[198:201], v[100:103]
	v_mfma_f32_16x16x32_bf16 v[96:99], v[182:185], v[198:201], v[96:99]
	v_mfma_f32_16x16x32_bf16 v[84:87], v[174:177], v[206:209], v[84:87]
	v_mfma_f32_16x16x32_bf16 v[80:83], v[182:185], v[206:209], v[80:83]
	v_mfma_f32_16x16x32_bf16 v[68:71], v[174:177], v[214:217], v[68:71]
	v_mfma_f32_16x16x32_bf16 v[64:67], v[182:185], v[214:217], v[64:67]
	s_setprio 0
	s_barrier
	s_add_i32 s40, s42, s85
	s_add_u32 s98, s60, s18
	s_addc_u32 s99, s61, s19
	s_mov_b32 m0, s40
	ds_read_b128 v[186:189], v156 offset:49152
	ds_read_b128 v[190:193], v156 offset:50176
	ds_read_b128 v[194:197], v156 offset:51200
	ds_read_b128 v[198:201], v156 offset:52224
	ds_read_b128 v[202:205], v156 offset:53248
	ds_read_b128 v[206:209], v156 offset:54272
	ds_read_b128 v[210:213], v156 offset:55296
	ds_read_b128 v[214:217], v156 offset:56320
	global_load_lds_dwordx4 v130, s[98:99]
	s_add_i32 m0, s40, 0x2000
	s_add_u32 s40, s60, 0x40080
	s_addc_u32 s41, s61, 0
	s_add_i32 s42, s43, s85
	global_load_lds_dwordx4 v134, s[98:99]
	s_mov_b32 m0, s42
	s_add_u32 s100, s62, s18
	s_addc_u32 s101, s63, s19
	global_load_lds_dwordx4 v130, s[40:41]
	s_add_i32 m0, s42, 0x2000
	s_nop 0
	global_load_lds_dwordx4 v134, s[40:41]
	s_mov_b32 m0, s30
	s_nop 0
	global_load_lds_dwordx4 v128, s[100:101]
	s_mov_b32 m0, s31
	s_nop 0
	global_load_lds_dwordx4 v132, s[100:101]
	s_waitcnt vmcnt(8)
	s_waitcnt lgkmcnt(0)
	s_barrier
	s_setprio 1
	s_waitcnt lgkmcnt(0)
	v_mfma_f32_16x16x32_bf16 v[60:63], v[148:151], v[186:189], v[60:63]
	v_mfma_f32_16x16x32_bf16 v[56:59], v[162:165], v[186:189], v[56:59]
	v_mfma_f32_16x16x32_bf16 v[44:47], v[148:151], v[194:197], v[44:47]
	v_mfma_f32_16x16x32_bf16 v[40:43], v[162:165], v[194:197], v[40:43]
	v_mfma_f32_16x16x32_bf16 v[28:31], v[148:151], v[202:205], v[28:31]
	v_mfma_f32_16x16x32_bf16 v[24:27], v[162:165], v[202:205], v[24:27]
	v_mfma_f32_16x16x32_bf16 v[12:15], v[148:151], v[210:213], v[12:15]
	v_mfma_f32_16x16x32_bf16 v[8:11], v[162:165], v[210:213], v[8:11]
	v_mfma_f32_16x16x32_bf16 v[60:63], v[158:161], v[190:193], v[60:63]
	v_mfma_f32_16x16x32_bf16 v[56:59], v[166:169], v[190:193], v[56:59]
	v_mfma_f32_16x16x32_bf16 v[44:47], v[158:161], v[198:201], v[44:47]
	v_mfma_f32_16x16x32_bf16 v[40:43], v[166:169], v[198:201], v[40:43]
	v_mfma_f32_16x16x32_bf16 v[28:31], v[158:161], v[206:209], v[28:31]
	v_mfma_f32_16x16x32_bf16 v[24:27], v[166:169], v[206:209], v[24:27]
	v_mfma_f32_16x16x32_bf16 v[12:15], v[158:161], v[214:217], v[12:15]
	v_mfma_f32_16x16x32_bf16 v[8:11], v[166:169], v[214:217], v[8:11]
	s_setprio 0
	s_setprio 1
	v_mfma_f32_16x16x32_bf16 v[52:55], v[170:173], v[186:189], v[52:55]
	v_mfma_f32_16x16x32_bf16 v[48:51], v[178:181], v[186:189], v[48:51]
	v_mfma_f32_16x16x32_bf16 v[36:39], v[170:173], v[194:197], v[36:39]
	v_mfma_f32_16x16x32_bf16 v[32:35], v[178:181], v[194:197], v[32:35]
	v_mfma_f32_16x16x32_bf16 v[20:23], v[170:173], v[202:205], v[20:23]
	v_mfma_f32_16x16x32_bf16 v[16:19], v[178:181], v[202:205], v[16:19]
	v_mfma_f32_16x16x32_bf16 v[4:7], v[170:173], v[210:213], v[4:7]
	v_mfma_f32_16x16x32_bf16 v[0:3], v[178:181], v[210:213], v[0:3]
	v_mfma_f32_16x16x32_bf16 v[52:55], v[174:177], v[190:193], v[52:55]
	v_mfma_f32_16x16x32_bf16 v[48:51], v[182:185], v[190:193], v[48:51]
	v_mfma_f32_16x16x32_bf16 v[36:39], v[174:177], v[198:201], v[36:39]
	v_mfma_f32_16x16x32_bf16 v[32:35], v[182:185], v[198:201], v[32:35]
	v_mfma_f32_16x16x32_bf16 v[20:23], v[174:177], v[206:209], v[20:23]
	v_mfma_f32_16x16x32_bf16 v[16:19], v[182:185], v[206:209], v[16:19]
	v_mfma_f32_16x16x32_bf16 v[4:7], v[174:177], v[214:217], v[4:7]
	v_mfma_f32_16x16x32_bf16 v[0:3], v[182:185], v[214:217], v[0:3]
	s_setprio 0
	s_barrier
	s_add_i32 s39, s39, 2
	s_add_u32 s58, s58, 0x100
	s_addc_u32 s59, s59, 0
	s_add_u32 s37, s37, 0x100
	s_addc_u32 s38, s38, 0
	s_cmp_gt_u32 s39, 13
	s_cbranch_scc0 .LBB0_244
	s_and_b64 vcc, exec, s[52:53]
	s_cbranch_vccz .LBB0_247
	s_barrier

; #define LAS __attribute__((address_space(3)))
; __global__ void __launch_bounds__(NTHR, 2) hybrid_fwd(Args args) {
;     extern __shared__ __attribute__((aligned(16))) unsigned char lds_raw[];
;     LAS unsigned char* lds = (LAS unsigned char*)lds_raw;
;     const int G = gridDim.x, bx = blockIdx.x;
;     const int wv = __builtin_amdgcn_readfirstlane(threadIdx.x >> 6);
;     unsigned char* ws = args.ws; unsigned char* dout = (unsigned char*)args.out;
;     const int lo = args.ph_lo, hi = args.ph_hi;
	.amdhsa_kernel _Z10hybrid_fwd4Args
		.amdhsa_group_segment_fixed_size 0
		.amdhsa_private_segment_fixed_size 0
		.amdhsa_kernarg_size 488
		.amdhsa_user_sgpr_count 2
		.amdhsa_user_sgpr_dispatch_ptr 0
		.amdhsa_user_sgpr_queue_ptr 0
		.amdhsa_user_sgpr_kernarg_segment_ptr 1
		.amdhsa_user_sgpr_dispatch_id 0
		.amdhsa_user_sgpr_kernarg_preload_length 0
		.amdhsa_user_sgpr_kernarg_preload_offset 0
		.amdhsa_user_sgpr_private_segment_size 0
		.amdhsa_uses_dynamic_stack 0
		.amdhsa_enable_private_segment 0
		.amdhsa_system_sgpr_workgroup_id_x 1
		.amdhsa_system_sgpr_workgroup_id_y 0
		.amdhsa_system_sgpr_workgroup_id_z 0
		.amdhsa_system_sgpr_workgroup_info 0
		.amdhsa_system_vgpr_workitem_id 0
		.amdhsa_next_free_vgpr 256
		.amdhsa_next_free_sgpr 102
		.amdhsa_accum_offset 256
		.amdhsa_reserve_vcc 1
		.amdhsa_float_round_mode_32 0
		.amdhsa_float_round_mode_16_64 0
		.amdhsa_float_denorm_mode_32 3
		.amdhsa_float_denorm_mode_16_64 3
		.amdhsa_dx10_clamp 1
		.amdhsa_ieee_mode 1
		.amdhsa_fp16_overflow 0
		.amdhsa_tg_split 0
		.amdhsa_exception_fp_ieee_invalid_op 0
		.amdhsa_exception_fp_denorm_src 0
		.amdhsa_exception_fp_ieee_div_zero 0
		.amdhsa_exception_fp_ieee_overflow 0
		.amdhsa_exception_fp_ieee_underflow 0
		.amdhsa_exception_fp_ieee_inexact 0
		.amdhsa_exception_int_div_zero 0
	.end_amdhsa_kernel

; #define LAS __attribute__((address_space(3)))
; __global__ void __launch_bounds__(NTHR, 2) hybrid_fwd(Args args) {
;     extern __shared__ __attribute__((aligned(16))) unsigned char lds_raw[];
;     LAS unsigned char* lds = (LAS unsigned char*)lds_raw;
;     const int G = gridDim.x, bx = blockIdx.x;
;     const int wv = __builtin_amdgcn_readfirstlane(threadIdx.x >> 6);
;     unsigned char* ws = args.ws; unsigned char* dout = (unsigned char*)args.out;
;     const int lo = args.ph_lo, hi = args.ph_hi;
amdhsa.kernels:
  - .agpr_count:     0
    .args:
      - .offset:         0
        .size:           232
        .value_kind:     by_value
      - .offset:         232
        .size:           4
        .value_kind:     hidden_block_count_x
      - .offset:         236
        .size:           4
        .value_kind:     hidden_block_count_y
      - .offset:         240
        .size:           4
        .value_kind:     hidden_block_count_z
      - .offset:         244
        .size:           2
        .value_kind:     hidden_group_size_x
      - .offset:         246
        .size:           2
        .value_kind:     hidden_group_size_y
      - .offset:         248
        .size:           2
        .value_kind:     hidden_group_size_z
      - .offset:         250
        .size:           2
        .value_kind:     hidden_remainder_x
      - .offset:         252
        .size:           2
        .value_kind:     hidden_remainder_y
      - .offset:         254
        .size:           2
        .value_kind:     hidden_remainder_z
      - .offset:         272
        .size:           8
        .value_kind:     hidden_global_offset_x
      - .offset:         280
        .size:           8
        .value_kind:     hidden_global_offset_y
      - .offset:         288
        .size:           8
        .value_kind:     hidden_global_offset_z
      - .offset:         296
        .size:           2
        .value_kind:     hidden_grid_dims
      - .offset:         320
        .size:           8
        .value_kind:     hidden_multigrid_sync_arg
      - .offset:         352
        .size:           4
        .value_kind:     hidden_dynamic_lds_size
    .group_segment_fixed_size: 0
    .kernarg_segment_align: 8
    .kernarg_segment_size: 488
    .language:       OpenCL C
    .language_version:
      - 2
      - 0
    .max_flat_workgroup_size: 512
    .name:           _Z10hybrid_fwd4Args
    .private_segment_fixed_size: 0
    .sgpr_count:     108
    .sgpr_spill_count: 65
    .symbol:         _Z10hybrid_fwd4Args.kd
    .uniform_work_group_size: 1
    .uses_dynamic_stack: false
    .vgpr_count:     256
    .vgpr_spill_count: 0
    .wavefront_size: 64
